# P1 too: accumulator zeroing removed on non-first tiles (C=0 first-touch MFMAs in the peeled iteration)
# baseline (speedup 1.0000x reference)
;     __device__ __forceinline__ const char* a(const Unit& u) const { return (const char*)A + (size_t)u.pm * 2 * hA(); }
;     __device__ __forceinline__ const char* b(const Unit& u) const { return (const char*)Bt + (size_t)u.pn * 2 * hB() + (size_t)(u.pm >> gshift) * goff; }
;     __device__ __forceinline__ const char* a(const Unit& u) const { return (const char*)A + (size_t)u.pm * 2 * hA(); }
;     __device__ __forceinline__ const char* b(const Unit& u) const { return (const char*)Bt + (size_t)((u.pn >> 4) * 4096 + (u.pn & 15) * 16) * 1024 * 2 + (size_t)(u.pm >> 1) * 512; }
;     __device__ __forceinline__ const char* a(const Unit&) const { return (const char*)A; }
;     __device__ __forceinline__ const char* b(const Unit& u) const { return (const char*)Bt + ((size_t)(((u.pm >> 4) * 1024 + u.pn * 256) * 16 + (u.pm & 15)) * 512) * 2; }
;     __device__ __forceinline__ bool next(int i, Unit& o) const { if (i) return false; o = u; return true; }
;     ...
;         const bool has_next = S.next(ui + 1, nxt);
;         const char* nA = has_next ? g.a(nxt) : cA;
;         const char* nB = has_next ? g.b(nxt) : cB;
.LBB0_181:
	s_ashr_i32 s21, s20, 31
	s_lshl_b64 s[22:23], s[20:21], 20
	v_readlane_b32 s26, v254, 20
	v_readlane_b32 s27, v254, 21
	s_add_u32 s22, s26, s22
	s_addc_u32 s23, s27, s23
	s_and_b64 s[26:27], s[8:9], exec
	s_cselect_b32 s5, s23, s29
	s_cselect_b32 s7, s22, s28
	s_ashr_i32 s19, s18, 31
	s_lshl_b64 s[26:27], s[18:19], 20
	s_add_u32 s26, s24, s26
	s_addc_u32 s27, s25, s27
	s_and_b64 s[34:35], s[8:9], exec
	s_cselect_b32 s19, s27, s31
	s_cselect_b32 s21, s26, s30
	s_add_u32 s61, s30, 0x100
	s_addc_u32 s66, s31, 0
	s_mov_b32 s67, -2
	v_readlane_b32 s98, v252, 5
	s_sub_i32 s99, s54, 1
	s_lshl_b32 s99, s99, 11
	s_add_i32 s98, s98, s99
	s_and_b32 s98, s98, 0x1fff
	s_lshr_b32 s99, s98, 6
	s_and_b32 s98, s98, 63
	s_lshl_b32 s99, s99, 19
	s_lshl_b32 s98, s98, 7
	s_add_u32 s98, s98, s99
	v_readlane_b32 s100, v252, 0
	v_readlane_b32 s101, v252, 1
	s_add_u32 s98, s100, s98
	s_addc_u32 s99, s101, 0
	s_cmp_lt_u32 s54, 2
	s_cbranch_scc1 mk_zero_p1
	s_add_u32 s30, s28, 0x100
	s_addc_u32 s31, s29, 0
	s_cmp_eq_u32 s67, 28
	s_cselect_b32 s42, s7, s30
	s_cselect_b32 s43, s5, s31
	s_cselect_b32 s45, s19, s66
	s_cselect_b32 s44, s21, s61
	s_add_u32 s34, s42, 0x80
	s_addc_u32 s35, s43, 0
	s_add_u32 s36, s44, 0x80
	s_addc_u32 s37, s45, 0
	s_add_u32 s68, s28, 0x80080
	s_addc_u32 s69, s29, 0
	s_add_u32 s40, s42, 0x80000
	s_addc_u32 s41, s43, 0
	s_add_u32 s46, s44, 0x80000
	s_addc_u32 s47, s45, 0
	s_add_u32 s28, s44, 0x80080
	s_addc_u32 s29, s45, 0
	ds_read_b128 v[140:143], v133
	ds_read_b128 v[144:147], v133 offset:1024
	ds_read_b128 v[148:151], v133 offset:2048
	ds_read_b128 v[152:155], v133 offset:3072
	ds_read_b128 v[156:159], v135
	ds_read_b128 v[160:163], v135 offset:1024
	ds_read_b128 v[168:171], v135 offset:2048
	ds_read_b128 v[172:175], v135 offset:3072
	s_add_i32 m0, s38, 0xc000
	ds_read_b128 v[176:179], v164
	ds_read_b128 v[180:183], v164 offset:1024
	ds_read_b128 v[184:187], v164 offset:2048
	ds_read_b128 v[188:191], v164 offset:3072
	ds_read_b128 v[192:195], v164 offset:4096
	ds_read_b128 v[196:199], v164 offset:5120
	ds_read_b128 v[200:203], v164 offset:6144
	ds_read_b128 v[204:207], v164 offset:7168
	global_load_lds_dwordx4 v128, s[68:69]
	s_add_i32 m0, s38, 0xe000
	s_nop 0
	global_load_lds_dwordx4 v132, s[68:69]
	s_waitcnt vmcnt(36)
	s_waitcnt lgkmcnt(0)
	s_barrier
	s_setprio 1
	s_waitcnt lgkmcnt(0)
	v_mfma_f32_16x16x32_bf16 v[124:127], v[140:143], v[176:179], 0
	v_mov_b32_e32 v208, v210
	v_mfma_f32_16x16x32_bf16 v[120:123], v[148:151], v[176:179], 0
	v_mov_b32_e32 v209, v211
	v_mfma_f32_16x16x32_bf16 v[108:111], v[140:143], v[184:187], 0
	v_mov_b32_e32 v210, v212
	v_mfma_f32_16x16x32_bf16 v[104:107], v[148:151], v[184:187], 0
	v_mov_b32_e32 v211, v213
	v_mfma_f32_16x16x32_bf16 v[92:95], v[140:143], v[192:195], 0
	v_mov_b32_e32 v212, v214
	v_mfma_f32_16x16x32_bf16 v[88:91], v[148:151], v[192:195], 0
	v_mov_b32_e32 v213, v215
	v_mfma_f32_16x16x32_bf16 v[76:79], v[140:143], v[200:203], 0
	v_mov_b32_e32 v214, v216
	v_mfma_f32_16x16x32_bf16 v[72:75], v[148:151], v[200:203], 0
	v_mov_b32_e32 v215, v217
	v_mfma_f32_16x16x32_bf16 v[124:127], v[144:147], v[180:183], v[124:127]
	v_mov_b32_e32 v216, v218
	v_mfma_f32_16x16x32_bf16 v[120:123], v[152:155], v[180:183], v[120:123]
	v_mov_b32_e32 v217, v219
	v_mfma_f32_16x16x32_bf16 v[108:111], v[144:147], v[188:191], v[108:111]
	v_mov_b32_e32 v218, v220
	v_mfma_f32_16x16x32_bf16 v[104:107], v[152:155], v[188:191], v[104:107]
	v_mov_b32_e32 v219, v221
	v_mfma_f32_16x16x32_bf16 v[92:95], v[144:147], v[196:199], v[92:95]
	v_mov_b32_e32 v220, v222
	v_mfma_f32_16x16x32_bf16 v[88:91], v[152:155], v[196:199], v[88:91]
	v_mov_b32_e32 v221, v223
	v_mfma_f32_16x16x32_bf16 v[76:79], v[144:147], v[204:207], v[76:79]
	v_mov_b32_e32 v222, v224
	v_mfma_f32_16x16x32_bf16 v[72:75], v[152:155], v[204:207], v[72:75]
	v_mov_b32_e32 v223, v225
	s_setprio 0
	s_setprio 1
	v_mfma_f32_16x16x32_bf16 v[116:119], v[156:159], v[176:179], 0
	v_mov_b32_e32 v224, v226
	v_mfma_f32_16x16x32_bf16 v[112:115], v[168:171], v[176:179], 0
	v_mov_b32_e32 v225, v227
	v_mfma_f32_16x16x32_bf16 v[100:103], v[156:159], v[184:187], 0
	v_mov_b32_e32 v226, v228
	v_mfma_f32_16x16x32_bf16 v[96:99], v[168:171], v[184:187], 0
	v_mov_b32_e32 v227, v229
	v_mfma_f32_16x16x32_bf16 v[84:87], v[156:159], v[192:195], 0
	v_mov_b32_e32 v228, v230
	v_mfma_f32_16x16x32_bf16 v[80:83], v[168:171], v[192:195], 0
	v_mov_b32_e32 v229, v231
	v_mfma_f32_16x16x32_bf16 v[68:71], v[156:159], v[200:203], 0
	v_mov_b32_e32 v230, v232
	v_mfma_f32_16x16x32_bf16 v[64:67], v[168:171], v[200:203], 0
	v_mov_b32_e32 v231, v233
	v_mfma_f32_16x16x32_bf16 v[116:119], v[160:163], v[180:183], v[116:119]
	v_mov_b32_e32 v232, v234
	v_mfma_f32_16x16x32_bf16 v[112:115], v[172:175], v[180:183], v[112:115]
	v_mov_b32_e32 v233, v235
	v_mfma_f32_16x16x32_bf16 v[100:103], v[160:163], v[188:191], v[100:103]
	v_mov_b32_e32 v234, v236
	v_mfma_f32_16x16x32_bf16 v[96:99], v[172:175], v[188:191], v[96:99]
	v_mov_b32_e32 v235, v237
	v_mfma_f32_16x16x32_bf16 v[84:87], v[160:163], v[196:199], v[84:87]
	v_mov_b32_e32 v236, v238
	v_mfma_f32_16x16x32_bf16 v[80:83], v[172:175], v[196:199], v[80:83]
	v_mov_b32_e32 v237, v239
	v_mfma_f32_16x16x32_bf16 v[68:71], v[160:163], v[204:207], v[68:71]
	v_mfma_f32_16x16x32_bf16 v[64:67], v[172:175], v[204:207], v[64:67]
	s_setprio 0
	s_barrier
	s_add_i32 s68, s57, s33
	s_mov_b32 m0, s68
	ds_read_b128 v[176:179], v164 offset:16384
	ds_read_b128 v[180:183], v164 offset:17408
	ds_read_b128 v[184:187], v164 offset:18432
	ds_read_b128 v[188:191], v164 offset:19456
	ds_read_b128 v[192:195], v164 offset:20480
	ds_read_b128 v[196:199], v164 offset:21504
	ds_read_b128 v[200:203], v164 offset:22528
	ds_read_b128 v[204:207], v164 offset:23552
	global_load_lds_dwordx4 v166, s[44:45]
	s_add_i32 m0, s68, 0x2000
	s_nop 0
	global_load_lds_dwordx4 v134, s[44:45]
	s_add_i32 s44, s60, s33
	s_mov_b32 m0, s44
	s_nop 0
	global_load_lds_dwordx4 v166, s[46:47]
	s_add_i32 m0, s44, 0x2000
	s_nop 0
	global_load_lds_dwordx4 v134, s[46:47]
	s_mov_b32 m0, s38
	s_nop 0
	global_load_lds_dwordx4 v128, s[42:43]
	s_mov_b32 m0, s39
	s_nop 0
	global_load_lds_dwordx4 v132, s[42:43]
	global_load_dwordx2 v[238:239], v250, s[98:99] nt
	s_add_u32 s98, s98, 0x2000
	s_addc_u32 s99, s99, 0
	s_waitcnt vmcnt(37)
	s_waitcnt lgkmcnt(0)
	s_barrier
	s_setprio 1
	s_waitcnt lgkmcnt(0)
	v_mfma_f32_16x16x32_bf16 v[60:63], v[140:143], v[176:179], 0
	v_mfma_f32_16x16x32_bf16 v[56:59], v[148:151], v[176:179], 0
	v_mfma_f32_16x16x32_bf16 v[44:47], v[140:143], v[184:187], 0
	v_mfma_f32_16x16x32_bf16 v[40:43], v[148:151], v[184:187], 0
	v_mfma_f32_16x16x32_bf16 v[28:31], v[140:143], v[192:195], 0
	v_mfma_f32_16x16x32_bf16 v[24:27], v[148:151], v[192:195], 0
	v_mfma_f32_16x16x32_bf16 v[12:15], v[140:143], v[200:203], 0
	v_mfma_f32_16x16x32_bf16 v[8:11], v[148:151], v[200:203], 0
	v_mfma_f32_16x16x32_bf16 v[60:63], v[144:147], v[180:183], v[60:63]
	v_mfma_f32_16x16x32_bf16 v[56:59], v[152:155], v[180:183], v[56:59]
	v_mfma_f32_16x16x32_bf16 v[44:47], v[144:147], v[188:191], v[44:47]
	v_mfma_f32_16x16x32_bf16 v[40:43], v[152:155], v[188:191], v[40:43]
	v_mfma_f32_16x16x32_bf16 v[28:31], v[144:147], v[196:199], v[28:31]
	v_mfma_f32_16x16x32_bf16 v[24:27], v[152:155], v[196:199], v[24:27]
	v_mfma_f32_16x16x32_bf16 v[12:15], v[144:147], v[204:207], v[12:15]
	v_mfma_f32_16x16x32_bf16 v[8:11], v[152:155], v[204:207], v[8:11]
	s_setprio 0
	s_setprio 1
	v_mfma_f32_16x16x32_bf16 v[52:55], v[156:159], v[176:179], 0
	v_mfma_f32_16x16x32_bf16 v[48:51], v[168:171], v[176:179], 0
	v_mfma_f32_16x16x32_bf16 v[36:39], v[156:159], v[184:187], 0
	v_mfma_f32_16x16x32_bf16 v[32:35], v[168:171], v[184:187], 0
	v_mfma_f32_16x16x32_bf16 v[20:23], v[156:159], v[192:195], 0
	v_mfma_f32_16x16x32_bf16 v[16:19], v[168:171], v[192:195], 0
	v_mfma_f32_16x16x32_bf16 v[4:7], v[156:159], v[200:203], 0
	v_mfma_f32_16x16x32_bf16 v[0:3], v[168:171], v[200:203], 0
	v_mfma_f32_16x16x32_bf16 v[52:55], v[160:163], v[180:183], v[52:55]
	v_mfma_f32_16x16x32_bf16 v[48:51], v[172:175], v[180:183], v[48:51]
	v_mfma_f32_16x16x32_bf16 v[36:39], v[160:163], v[188:191], v[36:39]
	v_mfma_f32_16x16x32_bf16 v[32:35], v[172:175], v[188:191], v[32:35]
	v_mfma_f32_16x16x32_bf16 v[20:23], v[160:163], v[196:199], v[20:23]
	v_mfma_f32_16x16x32_bf16 v[16:19], v[172:175], v[196:199], v[16:19]
	v_mfma_f32_16x16x32_bf16 v[4:7], v[160:163], v[204:207], v[4:7]
	v_mfma_f32_16x16x32_bf16 v[0:3], v[172:175], v[204:207], v[0:3]
	s_setprio 0
	s_barrier
	s_add_i32 s42, 0, 0x18000
	v_add_u32_e32 v130, s42, v129
	s_add_i32 s43, 0, 0x1c000
	ds_read_b128 v[140:143], v130
	ds_read_b128 v[144:147], v130 offset:1024
	ds_read_b128 v[148:151], v130 offset:2048
	ds_read_b128 v[152:155], v130 offset:3072
	v_add_u32_e32 v130, s43, v129
	ds_read_b128 v[156:159], v130
	ds_read_b128 v[160:163], v130 offset:1024
	ds_read_b128 v[168:171], v130 offset:2048
	ds_read_b128 v[172:175], v130 offset:3072
	s_mov_b32 m0, s52
	ds_read_b128 v[176:179], v164 offset:32768
	ds_read_b128 v[180:183], v164 offset:33792
	ds_read_b128 v[184:187], v164 offset:34816
	ds_read_b128 v[188:191], v164 offset:35840
	ds_read_b128 v[192:195], v164 offset:36864
	ds_read_b128 v[196:199], v164 offset:37888
	ds_read_b128 v[200:203], v164 offset:38912
	ds_read_b128 v[204:207], v164 offset:39936
	global_load_lds_dwordx4 v128, s[40:41]
	s_mov_b32 m0, s53
	s_nop 0
	global_load_lds_dwordx4 v132, s[40:41]
	s_waitcnt vmcnt(9)
	s_waitcnt lgkmcnt(0)
	s_barrier
	s_setprio 1
	s_waitcnt lgkmcnt(0)
	v_mfma_f32_16x16x32_bf16 v[124:127], v[140:143], v[176:179], v[124:127]
	v_mfma_f32_16x16x32_bf16 v[120:123], v[148:151], v[176:179], v[120:123]
	v_mfma_f32_16x16x32_bf16 v[108:111], v[140:143], v[184:187], v[108:111]
	v_mfma_f32_16x16x32_bf16 v[104:107], v[148:151], v[184:187], v[104:107]
	v_mfma_f32_16x16x32_bf16 v[92:95], v[140:143], v[192:195], v[92:95]
	v_mfma_f32_16x16x32_bf16 v[88:91], v[148:151], v[192:195], v[88:91]
	v_mfma_f32_16x16x32_bf16 v[76:79], v[140:143], v[200:203], v[76:79]
	v_mfma_f32_16x16x32_bf16 v[72:75], v[148:151], v[200:203], v[72:75]
	v_mfma_f32_16x16x32_bf16 v[124:127], v[144:147], v[180:183], v[124:127]
	v_mfma_f32_16x16x32_bf16 v[120:123], v[152:155], v[180:183], v[120:123]
	v_mfma_f32_16x16x32_bf16 v[108:111], v[144:147], v[188:191], v[108:111]
	v_mfma_f32_16x16x32_bf16 v[104:107], v[152:155], v[188:191], v[104:107]
	v_mfma_f32_16x16x32_bf16 v[92:95], v[144:147], v[196:199], v[92:95]
	v_mfma_f32_16x16x32_bf16 v[88:91], v[152:155], v[196:199], v[88:91]
	v_mfma_f32_16x16x32_bf16 v[76:79], v[144:147], v[204:207], v[76:79]
	v_mfma_f32_16x16x32_bf16 v[72:75], v[152:155], v[204:207], v[72:75]
	s_setprio 0
	s_setprio 1
	v_mfma_f32_16x16x32_bf16 v[116:119], v[156:159], v[176:179], v[116:119]
	v_mfma_f32_16x16x32_bf16 v[112:115], v[168:171], v[176:179], v[112:115]
	v_mfma_f32_16x16x32_bf16 v[100:103], v[156:159], v[184:187], v[100:103]
	v_mfma_f32_16x16x32_bf16 v[96:99], v[168:171], v[184:187], v[96:99]
	v_mfma_f32_16x16x32_bf16 v[84:87], v[156:159], v[192:195], v[84:87]
	v_mfma_f32_16x16x32_bf16 v[80:83], v[168:171], v[192:195], v[80:83]
	v_mfma_f32_16x16x32_bf16 v[68:71], v[156:159], v[200:203], v[68:71]
	v_mfma_f32_16x16x32_bf16 v[64:67], v[168:171], v[200:203], v[64:67]
	v_mfma_f32_16x16x32_bf16 v[116:119], v[160:163], v[180:183], v[116:119]
	v_mfma_f32_16x16x32_bf16 v[112:115], v[172:175], v[180:183], v[112:115]
	v_mfma_f32_16x16x32_bf16 v[100:103], v[160:163], v[188:191], v[100:103]
	v_mfma_f32_16x16x32_bf16 v[96:99], v[172:175], v[188:191], v[96:99]
	v_mfma_f32_16x16x32_bf16 v[84:87], v[160:163], v[196:199], v[84:87]
	v_mfma_f32_16x16x32_bf16 v[80:83], v[172:175], v[196:199], v[80:83]
	v_mfma_f32_16x16x32_bf16 v[68:71], v[160:163], v[204:207], v[68:71]
	v_mfma_f32_16x16x32_bf16 v[64:67], v[172:175], v[204:207], v[64:67]
	s_setprio 0
	s_barrier
;     __device__ __forceinline__ const char* a(const Unit& u) const { return (const char*)A + (size_t)u.pm * 2 * hA(); }
;     __device__ __forceinline__ const char* b(const Unit& u) const { return (const char*)Bt + (size_t)u.pn * 2 * hB() + (size_t)(u.pm >> gshift) * goff; }
;     __device__ __forceinline__ const char* a(const Unit& u) const { return (const char*)A + (size_t)u.pm * 2 * hA(); }
;     __device__ __forceinline__ const char* b(const Unit& u) const { return (const char*)Bt + (size_t)((u.pn >> 4) * 4096 + (u.pn & 15) * 16) * 1024 * 2 + (size_t)(u.pm >> 1) * 512; }
;     __device__ __forceinline__ const char* a(const Unit&) const { return (const char*)A; }
;     __device__ __forceinline__ const char* b(const Unit& u) const { return (const char*)Bt + ((size_t)(((u.pm >> 4) * 1024 + u.pn * 256) * 16 + (u.pm & 15)) * 512) * 2; }
; #define PG8_MMA(ai, bj, At, Bt) do { __builtin_amdgcn_s_setprio(1); _Pragma("unroll") for (int m = 0; m < 4; ++m) _Pragma("unroll") for (int n = 0; n < 2; ++n) _Pragma("unroll") for (int k = 0; k < 2; ++k) \
;         acc[ai][bj][m][n] = __builtin_amdgcn_mfma_f32_16x16x32_bf16(Bt[n][k], At[m][k], acc[ai][bj][m][n], 0, 0, 0); __builtin_amdgcn_s_setprio(0); } while (0)
; #define PG8_MMA8(ai, bj, At, Bt) do { __builtin_amdgcn_s_setprio(1); _Pragma("unroll") for (int m = 0; m < 4; ++m) _Pragma("unroll") for (int n = 0; n < 2; ++n) \
;         acc[ai][bj][m][n] = __builtin_amdgcn_mfma_scale_f32_16x16x128_f8f6f4(PG8_CAT(Bt[n][0], Bt[n][1]), PG8_CAT(At[m][0], At[m][1]), acc[ai][bj][m][n], 0, 0, 0, 0, 0, 0); __builtin_amdgcn_s_setprio(0); } while (0)
;     ...
;     f32x4 acc[2][2][4][2];
; #pragma unroll
;     for (int a = 0; a < 2; ++a)
; #pragma unroll
;         for (int b = 0; b < 2; ++b)
; #pragma unroll
;             for (int m = 0; m < 4; ++m)
; #pragma unroll
;                 for (int n = 0; n < 2; ++n) acc[a][b][m][n] = (f32x4){0.f, 0.f, 0.f, 0.f};
;     ...
;         { const int tmid = (TSW > 0 && TSW < nt) ? TSW : nt;
;           _Pragma("unroll 1") for (int t = 0; t < tmid; t += 2) { PG8_BODY(PG8_MMA) }
;           if constexpr (TSW > 0) { _Pragma("unroll 1") for (int t = tmid; t < nt; t += 2) { PG8_BODY(PG8_MMA8) } } }
	s_add_i32 s40, s42, s33
	s_mov_b32 m0, s40
	ds_read_b128 v[176:179], v164 offset:49152
	ds_read_b128 v[180:183], v164 offset:50176
	ds_read_b128 v[184:187], v164 offset:51200
	ds_read_b128 v[188:191], v164 offset:52224
	ds_read_b128 v[192:195], v164 offset:53248
	ds_read_b128 v[196:199], v164 offset:54272
	ds_read_b128 v[200:203], v164 offset:55296
	ds_read_b128 v[204:207], v164 offset:56320
	global_load_lds_dwordx4 v166, s[36:37]
	s_add_i32 m0, s40, 0x2000
	s_nop 0
	global_load_lds_dwordx4 v134, s[36:37]
	s_add_i32 s36, s43, s33
	s_mov_b32 m0, s36
	s_nop 0
	global_load_lds_dwordx4 v166, s[28:29]
	s_add_i32 m0, s36, 0x2000
	s_nop 0
	global_load_lds_dwordx4 v134, s[28:29]
	s_mov_b32 m0, s14
	s_nop 0
	global_load_lds_dwordx4 v128, s[34:35]
	s_mov_b32 m0, s15
	s_nop 0
	global_load_lds_dwordx4 v132, s[34:35]
	s_waitcnt vmcnt(9)
	s_waitcnt lgkmcnt(0)
	s_barrier
	s_setprio 1
	s_waitcnt lgkmcnt(0)
	v_mfma_f32_16x16x32_bf16 v[60:63], v[140:143], v[176:179], v[60:63]
	v_mfma_f32_16x16x32_bf16 v[56:59], v[148:151], v[176:179], v[56:59]
	v_mfma_f32_16x16x32_bf16 v[44:47], v[140:143], v[184:187], v[44:47]
	v_mfma_f32_16x16x32_bf16 v[40:43], v[148:151], v[184:187], v[40:43]
	v_mfma_f32_16x16x32_bf16 v[28:31], v[140:143], v[192:195], v[28:31]
	v_mfma_f32_16x16x32_bf16 v[24:27], v[148:151], v[192:195], v[24:27]
	v_mfma_f32_16x16x32_bf16 v[12:15], v[140:143], v[200:203], v[12:15]
	v_mfma_f32_16x16x32_bf16 v[8:11], v[148:151], v[200:203], v[8:11]
	v_mfma_f32_16x16x32_bf16 v[60:63], v[144:147], v[180:183], v[60:63]
	v_mfma_f32_16x16x32_bf16 v[56:59], v[152:155], v[180:183], v[56:59]
	v_mfma_f32_16x16x32_bf16 v[44:47], v[144:147], v[188:191], v[44:47]
	v_mfma_f32_16x16x32_bf16 v[40:43], v[152:155], v[188:191], v[40:43]
	v_mfma_f32_16x16x32_bf16 v[28:31], v[144:147], v[196:199], v[28:31]
	v_mfma_f32_16x16x32_bf16 v[24:27], v[152:155], v[196:199], v[24:27]
	v_mfma_f32_16x16x32_bf16 v[12:15], v[144:147], v[204:207], v[12:15]
	v_mfma_f32_16x16x32_bf16 v[8:11], v[152:155], v[204:207], v[8:11]
	s_setprio 0
	s_setprio 1
	v_mfma_f32_16x16x32_bf16 v[52:55], v[156:159], v[176:179], v[52:55]
	v_mfma_f32_16x16x32_bf16 v[48:51], v[168:171], v[176:179], v[48:51]
	v_mfma_f32_16x16x32_bf16 v[36:39], v[156:159], v[184:187], v[36:39]
	v_mfma_f32_16x16x32_bf16 v[32:35], v[168:171], v[184:187], v[32:35]
	v_mfma_f32_16x16x32_bf16 v[20:23], v[156:159], v[192:195], v[20:23]
	v_mfma_f32_16x16x32_bf16 v[16:19], v[168:171], v[192:195], v[16:19]
	v_mfma_f32_16x16x32_bf16 v[4:7], v[156:159], v[200:203], v[4:7]
	v_mfma_f32_16x16x32_bf16 v[0:3], v[168:171], v[200:203], v[0:3]
	v_mfma_f32_16x16x32_bf16 v[52:55], v[160:163], v[180:183], v[52:55]
	v_mfma_f32_16x16x32_bf16 v[48:51], v[172:175], v[180:183], v[48:51]
	v_mfma_f32_16x16x32_bf16 v[36:39], v[160:163], v[188:191], v[36:39]
	v_mfma_f32_16x16x32_bf16 v[32:35], v[172:175], v[188:191], v[32:35]
	v_mfma_f32_16x16x32_bf16 v[20:23], v[160:163], v[196:199], v[20:23]
	v_mfma_f32_16x16x32_bf16 v[16:19], v[172:175], v[196:199], v[16:19]
	v_mfma_f32_16x16x32_bf16 v[4:7], v[160:163], v[204:207], v[4:7]
	v_mfma_f32_16x16x32_bf16 v[0:3], v[172:175], v[204:207], v[0:3]
	s_setprio 0
	s_barrier
	s_add_i32 s67, s67, 2
	s_add_u32 s61, s61, 0x100
	s_addc_u32 s66, s66, 0
	s_cmp_gt_u32 s67, 29
	s_mov_b64 s[28:29], s[30:31]
	s_branch .LBB0_182
mk_zero_p1:
	v_mov_b32_e32 v0, 0
	v_mov_b32_e32 v1, v0
	v_mov_b32_e32 v2, v0
	v_mov_b32_e32 v3, v0
	v_mov_b32_e32 v4, v0
	v_mov_b32_e32 v5, v0
	v_mov_b32_e32 v6, v0
	v_mov_b32_e32 v7, v0
	v_mov_b32_e32 v16, v0
	v_mov_b32_e32 v17, v0
	v_mov_b32_e32 v18, v0
	v_mov_b32_e32 v19, v0
	v_mov_b32_e32 v20, v0
	v_mov_b32_e32 v21, v0
	v_mov_b32_e32 v22, v0
	v_mov_b32_e32 v23, v0
	v_mov_b32_e32 v32, v0
	v_mov_b32_e32 v33, v0
	v_mov_b32_e32 v34, v0
	v_mov_b32_e32 v35, v0
	v_mov_b32_e32 v36, v0
	v_mov_b32_e32 v37, v0
	v_mov_b32_e32 v38, v0
	v_mov_b32_e32 v39, v0
	v_mov_b32_e32 v48, v0
	v_mov_b32_e32 v49, v0
	v_mov_b32_e32 v50, v0
	v_mov_b32_e32 v51, v0
	v_mov_b32_e32 v52, v0
	v_mov_b32_e32 v53, v0
	v_mov_b32_e32 v54, v0
	v_mov_b32_e32 v55, v0
	v_mov_b32_e32 v8, v0
	v_mov_b32_e32 v9, v0
	v_mov_b32_e32 v10, v0
	v_mov_b32_e32 v11, v0
	v_mov_b32_e32 v12, v0
	v_mov_b32_e32 v13, v0
	v_mov_b32_e32 v14, v0
	v_mov_b32_e32 v15, v0
	v_mov_b32_e32 v24, v0
	v_mov_b32_e32 v25, v0
	v_mov_b32_e32 v26, v0
	v_mov_b32_e32 v27, v0
	v_mov_b32_e32 v28, v0
	v_mov_b32_e32 v29, v0
	v_mov_b32_e32 v30, v0
	v_mov_b32_e32 v31, v0
	v_mov_b32_e32 v40, v0
	v_mov_b32_e32 v41, v0
	v_mov_b32_e32 v42, v0
	v_mov_b32_e32 v43, v0
	v_mov_b32_e32 v44, v0
	v_mov_b32_e32 v45, v0
	v_mov_b32_e32 v46, v0
	v_mov_b32_e32 v47, v0
	v_mov_b32_e32 v56, v0
	v_mov_b32_e32 v57, v0
	v_mov_b32_e32 v58, v0
	v_mov_b32_e32 v59, v0
	v_mov_b32_e32 v60, v0
	v_mov_b32_e32 v61, v0
	v_mov_b32_e32 v62, v0
	v_mov_b32_e32 v63, v0
	v_mov_b32_e32 v64, v0
	v_mov_b32_e32 v65, v0
	v_mov_b32_e32 v66, v0
	v_mov_b32_e32 v67, v0
	v_mov_b32_e32 v68, v0
	v_mov_b32_e32 v69, v0
	v_mov_b32_e32 v70, v0
	v_mov_b32_e32 v71, v0
	v_mov_b32_e32 v80, v0
	v_mov_b32_e32 v81, v0
	v_mov_b32_e32 v82, v0
	v_mov_b32_e32 v83, v0
	v_mov_b32_e32 v84, v0
	v_mov_b32_e32 v85, v0
	v_mov_b32_e32 v86, v0
	v_mov_b32_e32 v87, v0
	v_mov_b32_e32 v96, v0
	v_mov_b32_e32 v97, v0
	v_mov_b32_e32 v98, v0
	v_mov_b32_e32 v99, v0
	v_mov_b32_e32 v100, v0
	v_mov_b32_e32 v101, v0
	v_mov_b32_e32 v102, v0
	v_mov_b32_e32 v103, v0
	v_mov_b32_e32 v112, v0
	v_mov_b32_e32 v113, v0
	v_mov_b32_e32 v114, v0
	v_mov_b32_e32 v115, v0
	v_mov_b32_e32 v116, v0
	v_mov_b32_e32 v117, v0
	v_mov_b32_e32 v118, v0
	v_mov_b32_e32 v119, v0
	v_mov_b32_e32 v72, v0
	v_mov_b32_e32 v73, v0
	v_mov_b32_e32 v74, v0
	v_mov_b32_e32 v75, v0
	v_mov_b32_e32 v76, v0
	v_mov_b32_e32 v77, v0
	v_mov_b32_e32 v78, v0
	v_mov_b32_e32 v79, v0
	v_mov_b32_e32 v88, v0
	v_mov_b32_e32 v89, v0
	v_mov_b32_e32 v90, v0
	v_mov_b32_e32 v91, v0
	v_mov_b32_e32 v92, v0
	v_mov_b32_e32 v93, v0
	v_mov_b32_e32 v94, v0
	v_mov_b32_e32 v95, v0
	v_mov_b32_e32 v104, v0
	v_mov_b32_e32 v105, v0
	v_mov_b32_e32 v106, v0
	v_mov_b32_e32 v107, v0
	v_mov_b32_e32 v108, v0
	v_mov_b32_e32 v109, v0
	v_mov_b32_e32 v110, v0
	v_mov_b32_e32 v111, v0
	v_mov_b32_e32 v120, v0
	v_mov_b32_e32 v121, v0
	v_mov_b32_e32 v122, v0
	v_mov_b32_e32 v123, v0
	v_mov_b32_e32 v124, v0
	v_mov_b32_e32 v125, v0
	v_mov_b32_e32 v126, v0
	v_mov_b32_e32 v127, v0
